# ffn_up K-loops: mid-segment s_waitcnt lgkmcnt(0) between the B and A fragment ds_read batches dropped (reads pipeline; closing lgkmcnt(0) before the barrier covers both)
# speedup vs baseline: 1.0021x; 1.0021x over previous
.LBB0_435:
	ds_read_b128 v[148:151], v222
	ds_read_b128 v[152:155], v222 offset:1024
	ds_read_b128 v[156:159], v222 offset:2048
	ds_read_b128 v[160:163], v222 offset:3072
	ds_read_b128 v[132:135], v223
	ds_read_b128 v[136:139], v223 offset:1024
	ds_read_b128 v[140:143], v223 offset:2048
	ds_read_b128 v[144:147], v223 offset:3072
	s_add_u32 s10, s54, 0xfff80080
	s_addc_u32 s11, s55, -1
	s_cmp_eq_u32 s84, 28
	s_cselect_b32 s59, s25, s11
	s_cselect_b32 s58, s46, s10
	s_cselect_b32 s57, s23, s83
	s_cselect_b32 s56, s47, s82
	v_lshl_add_u64 v[2:3], s[54:55], 0, v[208:209]
	s_add_i32 m0, s37, 0xc000
	ds_read_b128 v[164:167], v224
	ds_read_b128 v[168:171], v224 offset:1024
	ds_read_b128 v[172:175], v224 offset:2048
	ds_read_b128 v[176:179], v224 offset:3072
	ds_read_b128 v[180:183], v224 offset:4096
	ds_read_b128 v[184:187], v224 offset:5120
	ds_read_b128 v[188:191], v224 offset:6144
	ds_read_b128 v[192:195], v224 offset:7168
	global_load_lds_dwordx4 v[2:3], off
	v_lshl_add_u64 v[2:3], s[54:55], 0, v[206:207]
	s_add_i32 m0, s37, 0xe000
	s_nop 0
	global_load_lds_dwordx4 v[2:3], off
	s_waitcnt vmcnt(8)
	s_waitcnt lgkmcnt(0)
	s_barrier
	v_mfma_f32_16x16x32_bf16 v[120:123], v[148:151], v[164:167], v[120:123]
	v_mfma_f32_16x16x32_bf16 v[116:119], v[156:159], v[164:167], v[116:119]
	v_mfma_f32_16x16x32_bf16 v[104:107], v[148:151], v[172:175], v[104:107]
	v_mfma_f32_16x16x32_bf16 v[100:103], v[156:159], v[172:175], v[100:103]
	v_mfma_f32_16x16x32_bf16 v[88:91], v[148:151], v[180:183], v[88:91]
	v_mfma_f32_16x16x32_bf16 v[84:87], v[156:159], v[180:183], v[84:87]
	v_mfma_f32_16x16x32_bf16 v[76:79], v[148:151], v[188:191], v[76:79]
	v_mfma_f32_16x16x32_bf16 v[72:75], v[156:159], v[188:191], v[72:75]
	v_mfma_f32_16x16x32_bf16 v[120:123], v[152:155], v[168:171], v[120:123]
	v_mfma_f32_16x16x32_bf16 v[116:119], v[160:163], v[168:171], v[116:119]
	v_mfma_f32_16x16x32_bf16 v[104:107], v[152:155], v[176:179], v[104:107]
	v_mfma_f32_16x16x32_bf16 v[100:103], v[160:163], v[176:179], v[100:103]
	v_mfma_f32_16x16x32_bf16 v[88:91], v[152:155], v[184:187], v[88:91]
	v_mfma_f32_16x16x32_bf16 v[84:87], v[160:163], v[184:187], v[84:87]
	v_mfma_f32_16x16x32_bf16 v[76:79], v[152:155], v[192:195], v[76:79]
	v_mfma_f32_16x16x32_bf16 v[72:75], v[160:163], v[192:195], v[72:75]
	v_mfma_f32_16x16x32_bf16 v[128:131], v[132:135], v[164:167], v[128:131]
	v_mfma_f32_16x16x32_bf16 v[124:127], v[140:143], v[164:167], v[124:127]
	v_mfma_f32_16x16x32_bf16 v[112:115], v[132:135], v[172:175], v[112:115]
	v_mfma_f32_16x16x32_bf16 v[108:111], v[140:143], v[172:175], v[108:111]
	v_mfma_f32_16x16x32_bf16 v[96:99], v[132:135], v[180:183], v[96:99]
	v_mfma_f32_16x16x32_bf16 v[92:95], v[140:143], v[180:183], v[92:95]
	v_mfma_f32_16x16x32_bf16 v[80:83], v[132:135], v[188:191], v[80:83]
	v_mfma_f32_16x16x32_bf16 v[68:71], v[140:143], v[188:191], v[68:71]
	v_mfma_f32_16x16x32_bf16 v[128:131], v[136:139], v[168:171], v[128:131]
	v_mfma_f32_16x16x32_bf16 v[124:127], v[144:147], v[168:171], v[124:127]
	v_mfma_f32_16x16x32_bf16 v[112:115], v[136:139], v[176:179], v[112:115]
	v_mfma_f32_16x16x32_bf16 v[108:111], v[144:147], v[176:179], v[108:111]
	v_mfma_f32_16x16x32_bf16 v[96:99], v[136:139], v[184:187], v[96:99]
	v_mfma_f32_16x16x32_bf16 v[92:95], v[144:147], v[184:187], v[92:95]
	v_mfma_f32_16x16x32_bf16 v[80:83], v[136:139], v[192:195], v[80:83]
	v_mfma_f32_16x16x32_bf16 v[68:71], v[144:147], v[192:195], v[68:71]
	s_barrier
	s_add_i32 s10, s67, s48
	v_lshl_add_u64 v[2:3], s[56:57], 0, v[198:199]
	s_mov_b32 m0, s10
	ds_read_b128 v[188:191], v224 offset:16384
	ds_read_b128 v[192:195], v224 offset:17408
	ds_read_b128 v[180:183], v224 offset:18432
	ds_read_b128 v[184:187], v224 offset:19456
	ds_read_b128 v[172:175], v224 offset:20480
	ds_read_b128 v[176:179], v224 offset:21504
	ds_read_b128 v[164:167], v224 offset:22528
	ds_read_b128 v[168:171], v224 offset:23552
	global_load_lds_dwordx4 v[2:3], off
	s_add_i32 m0, s10, 0x2000
	s_add_u32 s10, s56, 0x80000
	v_lshl_add_u64 v[212:213], s[56:57], 0, v[202:203]
	s_addc_u32 s11, s57, 0
	s_add_i32 s78, s70, s48
	global_load_lds_dwordx4 v[212:213], off
	v_lshl_add_u64 v[214:215], s[10:11], 0, v[198:199]
	s_mov_b32 m0, s78
	v_lshl_add_u64 v[216:217], s[58:59], 0, v[200:201]
	global_load_lds_dwordx4 v[214:215], off
	v_lshl_add_u64 v[214:215], s[10:11], 0, v[202:203]
	s_add_i32 m0, s78, 0x2000
	v_cmp_ne_u32_e64 s[10:11], 1, v227
	global_load_lds_dwordx4 v[214:215], off
	v_lshl_add_u64 v[214:215], s[58:59], 0, v[196:197]
	s_mov_b32 m0, s37
	s_andn2_b64 vcc, exec, s[52:53]
	global_load_lds_dwordx4 v[214:215], off
	s_mov_b32 m0, s60
	s_nop 0
	global_load_lds_dwordx4 v[216:217], off
	s_waitcnt vmcnt(8)
	s_waitcnt lgkmcnt(0)
	s_cbranch_vccnz .Lsegskip_0
	s_barrier
	v_mfma_f32_16x16x32_bf16 v[56:59], v[148:151], v[188:191], v[56:59]
	v_mfma_f32_16x16x32_bf16 v[52:55], v[156:159], v[188:191], v[52:55]
	v_mfma_f32_16x16x32_bf16 v[40:43], v[148:151], v[180:183], v[40:43]
	v_mfma_f32_16x16x32_bf16 v[36:39], v[156:159], v[180:183], v[36:39]
	v_mfma_f32_16x16x32_bf16 v[24:27], v[148:151], v[172:175], v[24:27]
	v_mfma_f32_16x16x32_bf16 v[20:23], v[156:159], v[172:175], v[20:23]
	v_mfma_f32_16x16x32_bf16 v[8:11], v[148:151], v[164:167], v[8:11]
	v_mfma_f32_16x16x32_bf16 v[4:7], v[156:159], v[164:167], v[4:7]
	v_mfma_f32_16x16x32_bf16 v[56:59], v[152:155], v[192:195], v[56:59]
	v_mfma_f32_16x16x32_bf16 v[52:55], v[160:163], v[192:195], v[52:55]
	v_mfma_f32_16x16x32_bf16 v[40:43], v[152:155], v[184:187], v[40:43]
	v_mfma_f32_16x16x32_bf16 v[36:39], v[160:163], v[184:187], v[36:39]
	v_mfma_f32_16x16x32_bf16 v[24:27], v[152:155], v[176:179], v[24:27]
	v_mfma_f32_16x16x32_bf16 v[20:23], v[160:163], v[176:179], v[20:23]
	v_mfma_f32_16x16x32_bf16 v[8:11], v[152:155], v[168:171], v[8:11]
	v_mfma_f32_16x16x32_bf16 v[4:7], v[160:163], v[168:171], v[4:7]
	v_mfma_f32_16x16x32_bf16 v[64:67], v[132:135], v[188:191], v[64:67]
	v_mfma_f32_16x16x32_bf16 v[60:63], v[140:143], v[188:191], v[60:63]
	v_mfma_f32_16x16x32_bf16 v[48:51], v[132:135], v[180:183], v[48:51]
	v_mfma_f32_16x16x32_bf16 v[44:47], v[140:143], v[180:183], v[44:47]
	v_mfma_f32_16x16x32_bf16 v[32:35], v[132:135], v[172:175], v[32:35]
	v_mfma_f32_16x16x32_bf16 v[28:31], v[140:143], v[172:175], v[28:31]
	v_mfma_f32_16x16x32_bf16 v[16:19], v[132:135], v[164:167], v[16:19]
	v_mfma_f32_16x16x32_bf16 v[12:15], v[140:143], v[164:167], v[12:15]
	v_mfma_f32_16x16x32_bf16 v[64:67], v[136:139], v[192:195], v[64:67]
	v_mfma_f32_16x16x32_bf16 v[60:63], v[144:147], v[192:195], v[60:63]
	v_mfma_f32_16x16x32_bf16 v[48:51], v[136:139], v[184:187], v[48:51]
	v_mfma_f32_16x16x32_bf16 v[44:47], v[144:147], v[184:187], v[44:47]
	v_mfma_f32_16x16x32_bf16 v[32:35], v[136:139], v[176:179], v[32:35]
	v_mfma_f32_16x16x32_bf16 v[28:31], v[144:147], v[176:179], v[28:31]
	v_mfma_f32_16x16x32_bf16 v[16:19], v[136:139], v[168:171], v[16:19]
	v_mfma_f32_16x16x32_bf16 v[12:15], v[144:147], v[168:171], v[12:15]
.LBB0_437:
	s_barrier
	s_add_i32 s78, 0, 0x18000
	v_add_u32_e32 v1, s78, v220
	s_add_i32 s79, 0, 0x1c000
	ds_read_b128 v[148:151], v1
	ds_read_b128 v[152:155], v1 offset:1024
	ds_read_b128 v[156:159], v1 offset:2048
	ds_read_b128 v[160:163], v1 offset:3072
	v_add_u32_e32 v1, s79, v220
	ds_read_b128 v[132:135], v1
	ds_read_b128 v[136:139], v1 offset:1024
	ds_read_b128 v[140:143], v1 offset:2048
	ds_read_b128 v[144:147], v1 offset:3072
	s_add_u32 s58, s58, 0x80000
	s_addc_u32 s59, s59, 0
	s_mov_b32 m0, s61
	v_lshl_add_u64 v[228:229], s[58:59], 0, v[196:197]
	ds_read_b128 v[164:167], v224 offset:32768
	ds_read_b128 v[168:171], v224 offset:33792
	ds_read_b128 v[172:175], v224 offset:34816
	ds_read_b128 v[176:179], v224 offset:35840
	ds_read_b128 v[180:183], v224 offset:36864
	ds_read_b128 v[184:187], v224 offset:37888
	ds_read_b128 v[188:191], v224 offset:38912
	ds_read_b128 v[192:195], v224 offset:39936
	global_load_lds_dwordx4 v[228:229], off
	v_lshl_add_u64 v[228:229], s[58:59], 0, v[200:201]
	s_mov_b32 m0, s62
	s_nop 0
	global_load_lds_dwordx4 v[228:229], off
	s_waitcnt vmcnt(8)
	s_waitcnt lgkmcnt(0)
	s_barrier
	v_mfma_f32_16x16x32_bf16 v[120:123], v[148:151], v[164:167], v[120:123]
	v_mfma_f32_16x16x32_bf16 v[116:119], v[156:159], v[164:167], v[116:119]
	v_mfma_f32_16x16x32_bf16 v[104:107], v[148:151], v[172:175], v[104:107]
	v_mfma_f32_16x16x32_bf16 v[100:103], v[156:159], v[172:175], v[100:103]
	v_mfma_f32_16x16x32_bf16 v[88:91], v[148:151], v[180:183], v[88:91]
	v_mfma_f32_16x16x32_bf16 v[84:87], v[156:159], v[180:183], v[84:87]
	v_mfma_f32_16x16x32_bf16 v[76:79], v[148:151], v[188:191], v[76:79]
	v_mfma_f32_16x16x32_bf16 v[72:75], v[156:159], v[188:191], v[72:75]
	v_mfma_f32_16x16x32_bf16 v[120:123], v[152:155], v[168:171], v[120:123]
	v_mfma_f32_16x16x32_bf16 v[116:119], v[160:163], v[168:171], v[116:119]
	v_mfma_f32_16x16x32_bf16 v[104:107], v[152:155], v[176:179], v[104:107]
	v_mfma_f32_16x16x32_bf16 v[100:103], v[160:163], v[176:179], v[100:103]
	v_mfma_f32_16x16x32_bf16 v[88:91], v[152:155], v[184:187], v[88:91]
	v_mfma_f32_16x16x32_bf16 v[84:87], v[160:163], v[184:187], v[84:87]
	v_mfma_f32_16x16x32_bf16 v[76:79], v[152:155], v[192:195], v[76:79]
	v_mfma_f32_16x16x32_bf16 v[72:75], v[160:163], v[192:195], v[72:75]
	v_mfma_f32_16x16x32_bf16 v[128:131], v[132:135], v[164:167], v[128:131]
	v_mfma_f32_16x16x32_bf16 v[124:127], v[140:143], v[164:167], v[124:127]
	v_mfma_f32_16x16x32_bf16 v[112:115], v[132:135], v[172:175], v[112:115]
	v_mfma_f32_16x16x32_bf16 v[108:111], v[140:143], v[172:175], v[108:111]
	v_mfma_f32_16x16x32_bf16 v[96:99], v[132:135], v[180:183], v[96:99]
	v_mfma_f32_16x16x32_bf16 v[92:95], v[140:143], v[180:183], v[92:95]
	v_mfma_f32_16x16x32_bf16 v[80:83], v[132:135], v[188:191], v[80:83]
	v_mfma_f32_16x16x32_bf16 v[68:71], v[140:143], v[188:191], v[68:71]
	v_mfma_f32_16x16x32_bf16 v[128:131], v[136:139], v[168:171], v[128:131]
	v_mfma_f32_16x16x32_bf16 v[124:127], v[144:147], v[168:171], v[124:127]
	v_mfma_f32_16x16x32_bf16 v[112:115], v[136:139], v[176:179], v[112:115]
	v_mfma_f32_16x16x32_bf16 v[108:111], v[144:147], v[176:179], v[108:111]
	v_mfma_f32_16x16x32_bf16 v[96:99], v[136:139], v[184:187], v[96:99]
	v_mfma_f32_16x16x32_bf16 v[92:95], v[144:147], v[184:187], v[92:95]
	v_mfma_f32_16x16x32_bf16 v[80:83], v[136:139], v[192:195], v[80:83]
	v_mfma_f32_16x16x32_bf16 v[68:71], v[144:147], v[192:195], v[68:71]
	s_barrier
	s_add_i32 s58, s78, s48
	v_lshl_add_u64 v[2:3], v[2:3], 0, s[16:17]
	s_mov_b32 m0, s58
	ds_read_b128 v[188:191], v224 offset:49152
	ds_read_b128 v[192:195], v224 offset:50176
	ds_read_b128 v[180:183], v224 offset:51200
	ds_read_b128 v[184:187], v224 offset:52224
	ds_read_b128 v[172:175], v224 offset:53248
	ds_read_b128 v[176:179], v224 offset:54272
	ds_read_b128 v[164:167], v224 offset:55296
	ds_read_b128 v[168:171], v224 offset:56320
	global_load_lds_dwordx4 v[2:3], off
	s_add_i32 m0, s58, 0x2000
	s_add_u32 s56, s56, 0x80080
	v_lshl_add_u64 v[2:3], v[212:213], 0, s[16:17]
	s_addc_u32 s57, s57, 0
	s_add_i32 s58, s79, s48
	global_load_lds_dwordx4 v[2:3], off
	v_lshl_add_u64 v[2:3], s[56:57], 0, v[198:199]
	s_mov_b32 m0, s58
	s_and_b64 vcc, exec, s[10:11]
	global_load_lds_dwordx4 v[2:3], off
	v_lshl_add_u64 v[2:3], s[56:57], 0, v[202:203]
	s_add_i32 m0, s58, 0x2000
	s_nop 0
	global_load_lds_dwordx4 v[2:3], off
	v_lshl_add_u64 v[2:3], v[214:215], 0, s[16:17]
	s_mov_b32 m0, s63
	s_nop 0
	global_load_lds_dwordx4 v[2:3], off
	v_lshl_add_u64 v[2:3], v[216:217], 0, s[16:17]
	s_mov_b32 m0, s64
	s_nop 0
	global_load_lds_dwordx4 v[2:3], off
	s_waitcnt vmcnt(8)
	s_waitcnt lgkmcnt(0)
	s_cbranch_vccnz .Lsegskip_1
	s_barrier
	v_mfma_f32_16x16x32_bf16 v[56:59], v[148:151], v[188:191], v[56:59]
	v_mfma_f32_16x16x32_bf16 v[52:55], v[156:159], v[188:191], v[52:55]
	v_mfma_f32_16x16x32_bf16 v[40:43], v[148:151], v[180:183], v[40:43]
	v_mfma_f32_16x16x32_bf16 v[36:39], v[156:159], v[180:183], v[36:39]
	v_mfma_f32_16x16x32_bf16 v[24:27], v[148:151], v[172:175], v[24:27]
	v_mfma_f32_16x16x32_bf16 v[20:23], v[156:159], v[172:175], v[20:23]
	v_mfma_f32_16x16x32_bf16 v[8:11], v[148:151], v[164:167], v[8:11]
	v_mfma_f32_16x16x32_bf16 v[2:5], v[156:159], v[164:167], v[4:7]
	v_mfma_f32_16x16x32_bf16 v[56:59], v[152:155], v[192:195], v[56:59]
	v_mfma_f32_16x16x32_bf16 v[52:55], v[160:163], v[192:195], v[52:55]
	v_mfma_f32_16x16x32_bf16 v[40:43], v[152:155], v[184:187], v[40:43]
	v_mfma_f32_16x16x32_bf16 v[36:39], v[160:163], v[184:187], v[36:39]
	v_mfma_f32_16x16x32_bf16 v[24:27], v[152:155], v[176:179], v[24:27]
	v_mfma_f32_16x16x32_bf16 v[20:23], v[160:163], v[176:179], v[20:23]
	v_mfma_f32_16x16x32_bf16 v[8:11], v[152:155], v[168:171], v[8:11]
	v_mfma_f32_16x16x32_bf16 v[4:7], v[160:163], v[168:171], v[2:5]
	v_mfma_f32_16x16x32_bf16 v[64:67], v[132:135], v[188:191], v[64:67]
	v_mfma_f32_16x16x32_bf16 v[60:63], v[140:143], v[188:191], v[60:63]
	v_mfma_f32_16x16x32_bf16 v[48:51], v[132:135], v[180:183], v[48:51]
	v_mfma_f32_16x16x32_bf16 v[44:47], v[140:143], v[180:183], v[44:47]
	v_mfma_f32_16x16x32_bf16 v[32:35], v[132:135], v[172:175], v[32:35]
	v_mfma_f32_16x16x32_bf16 v[28:31], v[140:143], v[172:175], v[28:31]
	v_mfma_f32_16x16x32_bf16 v[16:19], v[132:135], v[164:167], v[16:19]
	v_mfma_f32_16x16x32_bf16 v[12:15], v[140:143], v[164:167], v[12:15]
	v_mfma_f32_16x16x32_bf16 v[64:67], v[136:139], v[192:195], v[64:67]
	v_mfma_f32_16x16x32_bf16 v[60:63], v[144:147], v[192:195], v[60:63]
	v_mfma_f32_16x16x32_bf16 v[48:51], v[136:139], v[184:187], v[48:51]
	v_mfma_f32_16x16x32_bf16 v[44:47], v[144:147], v[184:187], v[44:47]
	v_mfma_f32_16x16x32_bf16 v[32:35], v[136:139], v[176:179], v[32:35]
	v_mfma_f32_16x16x32_bf16 v[28:31], v[144:147], v[176:179], v[28:31]
	v_mfma_f32_16x16x32_bf16 v[16:19], v[136:139], v[168:171], v[16:19]
	v_mfma_f32_16x16x32_bf16 v[12:15], v[144:147], v[168:171], v[12:15]
	s_barrier
	s_branch .Lsegback_1

.LBB0_1049:
	ds_read_b128 v[148:151], v222
	ds_read_b128 v[152:155], v222 offset:1024
	ds_read_b128 v[156:159], v222 offset:2048
	ds_read_b128 v[160:163], v222 offset:3072
	ds_read_b128 v[132:135], v223
	ds_read_b128 v[136:139], v223 offset:1024
	ds_read_b128 v[140:143], v223 offset:2048
	ds_read_b128 v[144:147], v223 offset:3072
	s_add_u32 s8, s48, 0xfff80080
	s_addc_u32 s9, s49, -1
	s_cmp_eq_u32 s81, 28
	s_cselect_b32 s53, s23, s9
	s_cselect_b32 s52, s46, s8
	s_cselect_b32 s51, s21, s80
	s_cselect_b32 s50, s47, s79
	v_lshl_add_u64 v[2:3], s[48:49], 0, v[208:209]
	s_add_i32 m0, s35, 0xc000
	ds_read_b128 v[164:167], v224
	ds_read_b128 v[168:171], v224 offset:1024
	ds_read_b128 v[172:175], v224 offset:2048
	ds_read_b128 v[176:179], v224 offset:3072
	ds_read_b128 v[180:183], v224 offset:4096
	ds_read_b128 v[184:187], v224 offset:5120
	ds_read_b128 v[188:191], v224 offset:6144
	ds_read_b128 v[192:195], v224 offset:7168
	global_load_lds_dwordx4 v[2:3], off
	v_lshl_add_u64 v[2:3], s[48:49], 0, v[206:207]
	s_add_i32 m0, s35, 0xe000
	s_nop 0
	global_load_lds_dwordx4 v[2:3], off
	s_waitcnt vmcnt(8)
	s_waitcnt lgkmcnt(0)
	s_barrier
	v_mfma_f32_16x16x32_bf16 v[124:127], v[148:151], v[164:167], v[124:127]
	v_mfma_f32_16x16x32_bf16 v[120:123], v[156:159], v[164:167], v[120:123]
	v_mfma_f32_16x16x32_bf16 v[104:107], v[148:151], v[172:175], v[104:107]
	v_mfma_f32_16x16x32_bf16 v[100:103], v[156:159], v[172:175], v[100:103]
	v_mfma_f32_16x16x32_bf16 v[88:91], v[148:151], v[180:183], v[88:91]
	v_mfma_f32_16x16x32_bf16 v[84:87], v[156:159], v[180:183], v[84:87]
	v_mfma_f32_16x16x32_bf16 v[76:79], v[148:151], v[188:191], v[76:79]
	v_mfma_f32_16x16x32_bf16 v[72:75], v[156:159], v[188:191], v[72:75]
	v_mfma_f32_16x16x32_bf16 v[124:127], v[152:155], v[168:171], v[124:127]
	v_mfma_f32_16x16x32_bf16 v[120:123], v[160:163], v[168:171], v[120:123]
	v_mfma_f32_16x16x32_bf16 v[104:107], v[152:155], v[176:179], v[104:107]
	v_mfma_f32_16x16x32_bf16 v[100:103], v[160:163], v[176:179], v[100:103]
	v_mfma_f32_16x16x32_bf16 v[88:91], v[152:155], v[184:187], v[88:91]
	v_mfma_f32_16x16x32_bf16 v[84:87], v[160:163], v[184:187], v[84:87]
	v_mfma_f32_16x16x32_bf16 v[76:79], v[152:155], v[192:195], v[76:79]
	v_mfma_f32_16x16x32_bf16 v[72:75], v[160:163], v[192:195], v[72:75]
	v_mfma_f32_16x16x32_bf16 v[128:131], v[132:135], v[164:167], v[128:131]
	v_mfma_f32_16x16x32_bf16 v[116:119], v[140:143], v[164:167], v[116:119]
	v_mfma_f32_16x16x32_bf16 v[112:115], v[132:135], v[172:175], v[112:115]
	v_mfma_f32_16x16x32_bf16 v[108:111], v[140:143], v[172:175], v[108:111]
	v_mfma_f32_16x16x32_bf16 v[96:99], v[132:135], v[180:183], v[96:99]
	v_mfma_f32_16x16x32_bf16 v[92:95], v[140:143], v[180:183], v[92:95]
	v_mfma_f32_16x16x32_bf16 v[80:83], v[132:135], v[188:191], v[80:83]
	v_mfma_f32_16x16x32_bf16 v[68:71], v[140:143], v[188:191], v[68:71]
	v_mfma_f32_16x16x32_bf16 v[128:131], v[136:139], v[168:171], v[128:131]
	v_mfma_f32_16x16x32_bf16 v[116:119], v[144:147], v[168:171], v[116:119]
	v_mfma_f32_16x16x32_bf16 v[112:115], v[136:139], v[176:179], v[112:115]
	v_mfma_f32_16x16x32_bf16 v[108:111], v[144:147], v[176:179], v[108:111]
	v_mfma_f32_16x16x32_bf16 v[96:99], v[136:139], v[184:187], v[96:99]
	v_mfma_f32_16x16x32_bf16 v[92:95], v[144:147], v[184:187], v[92:95]
	v_mfma_f32_16x16x32_bf16 v[80:83], v[136:139], v[192:195], v[80:83]
	v_mfma_f32_16x16x32_bf16 v[68:71], v[144:147], v[192:195], v[68:71]
	s_barrier
	s_add_i32 s8, s65, s56
	v_lshl_add_u64 v[2:3], s[50:51], 0, v[198:199]
	s_mov_b32 m0, s8
	ds_read_b128 v[188:191], v224 offset:16384
	ds_read_b128 v[192:195], v224 offset:17408
	ds_read_b128 v[180:183], v224 offset:18432
	ds_read_b128 v[184:187], v224 offset:19456
	ds_read_b128 v[172:175], v224 offset:20480
	ds_read_b128 v[176:179], v224 offset:21504
	ds_read_b128 v[164:167], v224 offset:22528
	ds_read_b128 v[168:171], v224 offset:23552
	global_load_lds_dwordx4 v[2:3], off
	s_add_i32 m0, s8, 0x2000
	s_add_u32 s8, s50, 0x80000
	v_lshl_add_u64 v[212:213], s[50:51], 0, v[202:203]
	s_addc_u32 s9, s51, 0
	s_add_i32 s78, s66, s56
	global_load_lds_dwordx4 v[212:213], off
	v_lshl_add_u64 v[214:215], s[8:9], 0, v[198:199]
	s_mov_b32 m0, s78
	v_lshl_add_u64 v[216:217], s[52:53], 0, v[200:201]
	global_load_lds_dwordx4 v[214:215], off
	v_lshl_add_u64 v[214:215], s[8:9], 0, v[202:203]
	s_add_i32 m0, s78, 0x2000
	v_cmp_ne_u32_e64 s[8:9], 1, v227
	global_load_lds_dwordx4 v[214:215], off
	v_lshl_add_u64 v[214:215], s[52:53], 0, v[196:197]
	s_mov_b32 m0, s35
	s_andn2_b64 vcc, exec, s[36:37]
	global_load_lds_dwordx4 v[214:215], off
	s_mov_b32 m0, s58
	s_nop 0
	global_load_lds_dwordx4 v[216:217], off
	s_waitcnt vmcnt(8)
	s_waitcnt lgkmcnt(0)
	s_cbranch_vccnz .Lsegskip_2
	s_barrier
	v_mfma_f32_16x16x32_bf16 v[56:59], v[148:151], v[188:191], v[56:59]
	v_mfma_f32_16x16x32_bf16 v[52:55], v[156:159], v[188:191], v[52:55]
	v_mfma_f32_16x16x32_bf16 v[40:43], v[148:151], v[180:183], v[40:43]
	v_mfma_f32_16x16x32_bf16 v[36:39], v[156:159], v[180:183], v[36:39]
	v_mfma_f32_16x16x32_bf16 v[24:27], v[148:151], v[172:175], v[24:27]
	v_mfma_f32_16x16x32_bf16 v[20:23], v[156:159], v[172:175], v[20:23]
	v_mfma_f32_16x16x32_bf16 v[8:11], v[148:151], v[164:167], v[8:11]
	v_mfma_f32_16x16x32_bf16 v[4:7], v[156:159], v[164:167], v[4:7]
	v_mfma_f32_16x16x32_bf16 v[56:59], v[152:155], v[192:195], v[56:59]
	v_mfma_f32_16x16x32_bf16 v[52:55], v[160:163], v[192:195], v[52:55]
	v_mfma_f32_16x16x32_bf16 v[40:43], v[152:155], v[184:187], v[40:43]
	v_mfma_f32_16x16x32_bf16 v[36:39], v[160:163], v[184:187], v[36:39]
	v_mfma_f32_16x16x32_bf16 v[24:27], v[152:155], v[176:179], v[24:27]
	v_mfma_f32_16x16x32_bf16 v[20:23], v[160:163], v[176:179], v[20:23]
	v_mfma_f32_16x16x32_bf16 v[8:11], v[152:155], v[168:171], v[8:11]
	v_mfma_f32_16x16x32_bf16 v[4:7], v[160:163], v[168:171], v[4:7]
	v_mfma_f32_16x16x32_bf16 v[64:67], v[132:135], v[188:191], v[64:67]
	v_mfma_f32_16x16x32_bf16 v[60:63], v[140:143], v[188:191], v[60:63]
	v_mfma_f32_16x16x32_bf16 v[48:51], v[132:135], v[180:183], v[48:51]
	v_mfma_f32_16x16x32_bf16 v[44:47], v[140:143], v[180:183], v[44:47]
	v_mfma_f32_16x16x32_bf16 v[32:35], v[132:135], v[172:175], v[32:35]
	v_mfma_f32_16x16x32_bf16 v[28:31], v[140:143], v[172:175], v[28:31]
	v_mfma_f32_16x16x32_bf16 v[16:19], v[132:135], v[164:167], v[16:19]
	v_mfma_f32_16x16x32_bf16 v[12:15], v[140:143], v[164:167], v[12:15]
	v_mfma_f32_16x16x32_bf16 v[64:67], v[136:139], v[192:195], v[64:67]
	v_mfma_f32_16x16x32_bf16 v[60:63], v[144:147], v[192:195], v[60:63]
	v_mfma_f32_16x16x32_bf16 v[48:51], v[136:139], v[184:187], v[48:51]
	v_mfma_f32_16x16x32_bf16 v[44:47], v[144:147], v[184:187], v[44:47]
	v_mfma_f32_16x16x32_bf16 v[32:35], v[136:139], v[176:179], v[32:35]
	v_mfma_f32_16x16x32_bf16 v[28:31], v[144:147], v[176:179], v[28:31]
	v_mfma_f32_16x16x32_bf16 v[16:19], v[136:139], v[168:171], v[16:19]
	v_mfma_f32_16x16x32_bf16 v[12:15], v[144:147], v[168:171], v[12:15]
.LBB0_1051:
	s_barrier
	s_add_i32 s78, 0, 0x18000
	v_add_u32_e32 v1, s78, v220
	s_add_i32 s82, 0, 0x1c000
	ds_read_b128 v[148:151], v1
	ds_read_b128 v[152:155], v1 offset:1024
	ds_read_b128 v[156:159], v1 offset:2048
	ds_read_b128 v[160:163], v1 offset:3072
	v_add_u32_e32 v1, s82, v220
	ds_read_b128 v[132:135], v1
	ds_read_b128 v[136:139], v1 offset:1024
	ds_read_b128 v[140:143], v1 offset:2048
	ds_read_b128 v[144:147], v1 offset:3072
	s_add_u32 s52, s52, 0x80000
	s_addc_u32 s53, s53, 0
	s_mov_b32 m0, s59
	v_lshl_add_u64 v[228:229], s[52:53], 0, v[196:197]
	ds_read_b128 v[164:167], v224 offset:32768
	ds_read_b128 v[168:171], v224 offset:33792
	ds_read_b128 v[172:175], v224 offset:34816
	ds_read_b128 v[176:179], v224 offset:35840
	ds_read_b128 v[180:183], v224 offset:36864
	ds_read_b128 v[184:187], v224 offset:37888
	ds_read_b128 v[188:191], v224 offset:38912
	ds_read_b128 v[192:195], v224 offset:39936
	global_load_lds_dwordx4 v[228:229], off
	v_lshl_add_u64 v[228:229], s[52:53], 0, v[200:201]
	s_mov_b32 m0, s60
	s_nop 0
	global_load_lds_dwordx4 v[228:229], off
	s_waitcnt vmcnt(8)
	s_waitcnt lgkmcnt(0)
	s_barrier
	v_mfma_f32_16x16x32_bf16 v[124:127], v[148:151], v[164:167], v[124:127]
	v_mfma_f32_16x16x32_bf16 v[120:123], v[156:159], v[164:167], v[120:123]
	v_mfma_f32_16x16x32_bf16 v[104:107], v[148:151], v[172:175], v[104:107]
	v_mfma_f32_16x16x32_bf16 v[100:103], v[156:159], v[172:175], v[100:103]
	v_mfma_f32_16x16x32_bf16 v[88:91], v[148:151], v[180:183], v[88:91]
	v_mfma_f32_16x16x32_bf16 v[84:87], v[156:159], v[180:183], v[84:87]
	v_mfma_f32_16x16x32_bf16 v[76:79], v[148:151], v[188:191], v[76:79]
	v_mfma_f32_16x16x32_bf16 v[72:75], v[156:159], v[188:191], v[72:75]
	v_mfma_f32_16x16x32_bf16 v[124:127], v[152:155], v[168:171], v[124:127]
	v_mfma_f32_16x16x32_bf16 v[120:123], v[160:163], v[168:171], v[120:123]
	v_mfma_f32_16x16x32_bf16 v[104:107], v[152:155], v[176:179], v[104:107]
	v_mfma_f32_16x16x32_bf16 v[100:103], v[160:163], v[176:179], v[100:103]
	v_mfma_f32_16x16x32_bf16 v[88:91], v[152:155], v[184:187], v[88:91]
	v_mfma_f32_16x16x32_bf16 v[84:87], v[160:163], v[184:187], v[84:87]
	v_mfma_f32_16x16x32_bf16 v[76:79], v[152:155], v[192:195], v[76:79]
	v_mfma_f32_16x16x32_bf16 v[72:75], v[160:163], v[192:195], v[72:75]
	v_mfma_f32_16x16x32_bf16 v[128:131], v[132:135], v[164:167], v[128:131]
	v_mfma_f32_16x16x32_bf16 v[116:119], v[140:143], v[164:167], v[116:119]
	v_mfma_f32_16x16x32_bf16 v[112:115], v[132:135], v[172:175], v[112:115]
	v_mfma_f32_16x16x32_bf16 v[108:111], v[140:143], v[172:175], v[108:111]
	v_mfma_f32_16x16x32_bf16 v[96:99], v[132:135], v[180:183], v[96:99]
	v_mfma_f32_16x16x32_bf16 v[92:95], v[140:143], v[180:183], v[92:95]
	v_mfma_f32_16x16x32_bf16 v[80:83], v[132:135], v[188:191], v[80:83]
	v_mfma_f32_16x16x32_bf16 v[68:71], v[140:143], v[188:191], v[68:71]
	v_mfma_f32_16x16x32_bf16 v[128:131], v[136:139], v[168:171], v[128:131]
	v_mfma_f32_16x16x32_bf16 v[116:119], v[144:147], v[168:171], v[116:119]
	v_mfma_f32_16x16x32_bf16 v[112:115], v[136:139], v[176:179], v[112:115]
	v_mfma_f32_16x16x32_bf16 v[108:111], v[144:147], v[176:179], v[108:111]
	v_mfma_f32_16x16x32_bf16 v[96:99], v[136:139], v[184:187], v[96:99]
	v_mfma_f32_16x16x32_bf16 v[92:95], v[144:147], v[184:187], v[92:95]
	v_mfma_f32_16x16x32_bf16 v[80:83], v[136:139], v[192:195], v[80:83]
	v_mfma_f32_16x16x32_bf16 v[68:71], v[144:147], v[192:195], v[68:71]
	s_barrier
	s_add_i32 s52, s78, s56
	v_lshl_add_u64 v[2:3], v[2:3], 0, s[14:15]
	s_mov_b32 m0, s52
	ds_read_b128 v[188:191], v224 offset:49152
	ds_read_b128 v[192:195], v224 offset:50176
	ds_read_b128 v[180:183], v224 offset:51200
	ds_read_b128 v[184:187], v224 offset:52224
	ds_read_b128 v[172:175], v224 offset:53248
	ds_read_b128 v[176:179], v224 offset:54272
	ds_read_b128 v[164:167], v224 offset:55296
	ds_read_b128 v[168:171], v224 offset:56320
	global_load_lds_dwordx4 v[2:3], off
	s_add_i32 m0, s52, 0x2000
	s_add_u32 s50, s50, 0x80080
	v_lshl_add_u64 v[2:3], v[212:213], 0, s[14:15]
	s_addc_u32 s51, s51, 0
	s_add_i32 s52, s82, s56
	global_load_lds_dwordx4 v[2:3], off
	v_lshl_add_u64 v[2:3], s[50:51], 0, v[198:199]
	s_mov_b32 m0, s52
	s_and_b64 vcc, exec, s[8:9]
	global_load_lds_dwordx4 v[2:3], off
	v_lshl_add_u64 v[2:3], s[50:51], 0, v[202:203]
	s_add_i32 m0, s52, 0x2000
	s_nop 0
	global_load_lds_dwordx4 v[2:3], off
	v_lshl_add_u64 v[2:3], v[214:215], 0, s[14:15]
	s_mov_b32 m0, s61
	s_nop 0
	global_load_lds_dwordx4 v[2:3], off
	v_lshl_add_u64 v[2:3], v[216:217], 0, s[14:15]
	s_mov_b32 m0, s62
	s_nop 0
	global_load_lds_dwordx4 v[2:3], off
	s_waitcnt vmcnt(8)
	s_waitcnt lgkmcnt(0)
	s_cbranch_vccnz .Lsegskip_3
	s_barrier
	v_mfma_f32_16x16x32_bf16 v[56:59], v[148:151], v[188:191], v[56:59]
	v_mfma_f32_16x16x32_bf16 v[52:55], v[156:159], v[188:191], v[52:55]
	v_mfma_f32_16x16x32_bf16 v[40:43], v[148:151], v[180:183], v[40:43]
	v_mfma_f32_16x16x32_bf16 v[36:39], v[156:159], v[180:183], v[36:39]
	v_mfma_f32_16x16x32_bf16 v[24:27], v[148:151], v[172:175], v[24:27]
	v_mfma_f32_16x16x32_bf16 v[20:23], v[156:159], v[172:175], v[20:23]
	v_mfma_f32_16x16x32_bf16 v[8:11], v[148:151], v[164:167], v[8:11]
	v_mfma_f32_16x16x32_bf16 v[2:5], v[156:159], v[164:167], v[4:7]
	v_mfma_f32_16x16x32_bf16 v[56:59], v[152:155], v[192:195], v[56:59]
	v_mfma_f32_16x16x32_bf16 v[52:55], v[160:163], v[192:195], v[52:55]
	v_mfma_f32_16x16x32_bf16 v[40:43], v[152:155], v[184:187], v[40:43]
	v_mfma_f32_16x16x32_bf16 v[36:39], v[160:163], v[184:187], v[36:39]
	v_mfma_f32_16x16x32_bf16 v[24:27], v[152:155], v[176:179], v[24:27]
	v_mfma_f32_16x16x32_bf16 v[20:23], v[160:163], v[176:179], v[20:23]
	v_mfma_f32_16x16x32_bf16 v[8:11], v[152:155], v[168:171], v[8:11]
	v_mfma_f32_16x16x32_bf16 v[4:7], v[160:163], v[168:171], v[2:5]
	v_mfma_f32_16x16x32_bf16 v[64:67], v[132:135], v[188:191], v[64:67]
	v_mfma_f32_16x16x32_bf16 v[60:63], v[140:143], v[188:191], v[60:63]
	v_mfma_f32_16x16x32_bf16 v[48:51], v[132:135], v[180:183], v[48:51]
	v_mfma_f32_16x16x32_bf16 v[44:47], v[140:143], v[180:183], v[44:47]
	v_mfma_f32_16x16x32_bf16 v[32:35], v[132:135], v[172:175], v[32:35]
	v_mfma_f32_16x16x32_bf16 v[28:31], v[140:143], v[172:175], v[28:31]
	v_mfma_f32_16x16x32_bf16 v[16:19], v[132:135], v[164:167], v[16:19]
	v_mfma_f32_16x16x32_bf16 v[12:15], v[140:143], v[164:167], v[12:15]
	v_mfma_f32_16x16x32_bf16 v[64:67], v[136:139], v[192:195], v[64:67]
	v_mfma_f32_16x16x32_bf16 v[60:63], v[144:147], v[192:195], v[60:63]
	v_mfma_f32_16x16x32_bf16 v[48:51], v[136:139], v[184:187], v[48:51]
	v_mfma_f32_16x16x32_bf16 v[44:47], v[144:147], v[184:187], v[44:47]
	v_mfma_f32_16x16x32_bf16 v[32:35], v[136:139], v[176:179], v[32:35]
	v_mfma_f32_16x16x32_bf16 v[28:31], v[144:147], v[176:179], v[28:31]
	v_mfma_f32_16x16x32_bf16 v[16:19], v[136:139], v[168:171], v[16:19]
	v_mfma_f32_16x16x32_bf16 v[12:15], v[144:147], v[168:171], v[12:15]
	s_barrier
	s_branch .Lsegback_3
